# p-conversion loop unrolled 4x (8 loads in flight), on top of S5 rewrite
# baseline (speedup 1.0000x reference)
.LBB0_59:
	s_or_b64 exec, exec, s[10:11]
	v_readlane_b32 s2, v247, 0
	s_mov_b32 s1, 0x400000
	s_lshl_b32 s0, s66, 9
	v_lshl_add_u32 v2, s2, 9, v34
	v_cmp_gt_i32_e32 vcc, s1, v2
	v_lshlrev_b32_e32 v8, 1, v34
	v_readlane_b32 s3, v247, 1
	s_and_saveexec_b64 s[4:5], vcc
	s_mov_b32 s59, s87
	s_cbranch_execz .LBB0_62
	s_waitcnt lgkmcnt(1)
	v_ashrrev_i32_e32 v3, 31, v2
	v_readlane_b32 s2, v247, 0
	s_waitcnt lgkmcnt(0)
	v_lshl_add_u64 v[4:5], v[2:3], 4, s[90:91]
	s_mov_b64 s[6:7], 0xa800000
	s_ashr_i32 s1, s0, 31
	v_readlane_b32 s3, v247, 1
	v_lshl_add_u64 v[4:5], v[4:5], 0, s[6:7]
	s_lshl_b64 s[6:7], s[0:1], 4
	v_lshl_add_u32 v6, s2, 10, v8
	s_lshl_b32 s1, s66, 10
	s_mov_b64 s[10:11], 0
	s_mov_b32 s3, 0x3fffff
	v_mov_b32_e32 v1, v2
	s_cmpk_lg_i32 s66, 0x100
	s_cbranch_scc1 .LBB0_61
	s_mov_b64 s[20:21], 0x400000
	s_mov_b64 s[22:23], 0x200000
	s_mov_b64 s[12:13], 0x1000000
	s_mov_b64 s[14:15], 0x800000
	s_movk_i32 s24, 8
	v_mov_b32_e32 v7, 0
	v_mov_b32_e32 v112, v4
	v_mov_b32_e32 v113, v5
	v_lshl_add_u64 v[40:41], v[6:7], 4, s[18:19]
.Lp4_loop:
	v_lshl_add_u64 v[42:43], v[40:41], 0, s[20:21]
	v_lshl_add_u64 v[44:45], v[42:43], 0, s[20:21]
	v_lshl_add_u64 v[46:47], v[44:45], 0, s[20:21]
	global_load_dwordx4 v[80:83], v[40:41], off
	global_load_dwordx4 v[84:87], v[40:41], off offset:16
	global_load_dwordx4 v[88:91], v[42:43], off
	global_load_dwordx4 v[92:95], v[42:43], off offset:16
	global_load_dwordx4 v[96:99], v[44:45], off
	global_load_dwordx4 v[100:103], v[44:45], off offset:16
	global_load_dwordx4 v[104:107], v[46:47], off
	global_load_dwordx4 v[108:111], v[46:47], off offset:16
	v_lshl_add_u64 v[114:115], v[112:113], 0, s[22:23]
	v_lshl_add_u64 v[116:117], v[114:115], 0, s[22:23]
	v_lshl_add_u64 v[118:119], v[116:117], 0, s[22:23]
	v_lshl_add_u64 v[40:41], v[40:41], 0, s[12:13]
	s_waitcnt vmcnt(6)
	v_cvt_pk_bf16_f32 v80, v80, v81
	v_cvt_pk_bf16_f32 v81, v82, v83
	v_cvt_pk_bf16_f32 v82, v84, v85
	v_cvt_pk_bf16_f32 v83, v86, v87
	global_store_dwordx4 v[112:113], v[80:83], off
	s_waitcnt vmcnt(5)
	v_cvt_pk_bf16_f32 v88, v88, v89
	v_cvt_pk_bf16_f32 v89, v90, v91
	v_cvt_pk_bf16_f32 v90, v92, v93
	v_cvt_pk_bf16_f32 v91, v94, v95
	global_store_dwordx4 v[114:115], v[88:91], off
	s_waitcnt vmcnt(4)
	v_cvt_pk_bf16_f32 v96, v96, v97
	v_cvt_pk_bf16_f32 v97, v98, v99
	v_cvt_pk_bf16_f32 v98, v100, v101
	v_cvt_pk_bf16_f32 v99, v102, v103
	global_store_dwordx4 v[116:117], v[96:99], off
	s_waitcnt vmcnt(3)
	v_cvt_pk_bf16_f32 v104, v104, v105
	v_cvt_pk_bf16_f32 v105, v106, v107
	v_cvt_pk_bf16_f32 v106, v108, v109
	v_cvt_pk_bf16_f32 v107, v110, v111
	global_store_dwordx4 v[118:119], v[104:107], off
	v_lshl_add_u64 v[112:113], v[112:113], 0, s[14:15]
	s_sub_i32 s24, s24, 1
	s_cmp_lg_u32 s24, 0
	s_cbranch_scc1 .Lp4_loop
	s_branch .LBB0_62

.LBB0_655:
	s_mov_b32 s98, 0x3d372713
	s_mov_b32 s100, 0x3fcc422a
	s_mov_b32 s20, 0xbfb8aa3b
	s_mov_b32 s22, 1.0
	s_barrier
	v_and_b32_e32 v74, 63, v173
	v_and_b32_e32 v75, 15, v173
	s_lshl_b32 s24, s47, 13
	v_lshlrev_b32_e32 v75, 1, v75
	v_lshl_add_u32 v75, v198, 1, v75
	v_add_u32_e32 v75, s24, v75
	v_lshl_add_u32 v76, v74, 4, s24
	v_lshrrev_b32_e32 v77, 1, v74
	v_and_b32_e32 v74, 1, v74
	v_lshlrev_b32_e32 v77, 14, v77
	v_lshl_or_b32 v77, v74, 4, v77
	v_readfirstlane_b32 s18, v140
	v_readfirstlane_b32 s19, v141
	v_pk_mul_f32 v[2:3], v[114:115], s[98:99] op_sel_hi:[1,0]
	v_pk_mul_f32 v[2:3], v[114:115], v[2:3]
	v_pk_fma_f32 v[2:3], v[114:115], v[2:3], v[114:115]
	v_pk_mul_f32 v[2:3], v[2:3], s[100:101] op_sel_hi:[1,0]
	v_pk_mul_f32 v[2:3], v[2:3], s[20:21] op_sel_hi:[1,0]
	v_exp_f32_e32 v10, v2
	v_exp_f32_e32 v11, v3
	v_pk_mul_f32 v[4:5], v[116:117], s[98:99] op_sel_hi:[1,0]
	v_pk_mul_f32 v[4:5], v[116:117], v[4:5]
	v_pk_fma_f32 v[4:5], v[116:117], v[4:5], v[116:117]
	v_pk_mul_f32 v[4:5], v[4:5], s[100:101] op_sel_hi:[1,0]
	v_pk_mul_f32 v[4:5], v[4:5], s[20:21] op_sel_hi:[1,0]
	v_exp_f32_e32 v12, v4
	v_exp_f32_e32 v13, v5
	v_pk_add_f32 v[10:11], v[10:11], s[22:23] op_sel_hi:[1,0]
	v_rcp_f32_e32 v10, v10
	v_rcp_f32_e32 v11, v11
	v_pk_mul_f32 v[6:7], v[102:103], s[98:99] op_sel_hi:[1,0]
	v_pk_mul_f32 v[6:7], v[102:103], v[6:7]
	v_pk_fma_f32 v[6:7], v[102:103], v[6:7], v[102:103]
	v_pk_mul_f32 v[6:7], v[6:7], s[100:101] op_sel_hi:[1,0]
	v_pk_mul_f32 v[6:7], v[6:7], s[20:21] op_sel_hi:[1,0]
	v_exp_f32_e32 v14, v6
	v_exp_f32_e32 v15, v7
	v_pk_add_f32 v[12:13], v[12:13], s[22:23] op_sel_hi:[1,0]
	v_rcp_f32_e32 v12, v12
	v_rcp_f32_e32 v13, v13
	v_pk_mul_f32 v[10:11], v[114:115], v[10:11]
	v_cvt_pk_bf16_f32 v18, v10, v11
	ds_write_b16 v75, v18
	ds_write_b16_d16_hi v75, v18 offset:32
	v_pk_mul_f32 v[8:9], v[104:105], s[98:99] op_sel_hi:[1,0]
	v_pk_mul_f32 v[8:9], v[104:105], v[8:9]
	v_pk_fma_f32 v[8:9], v[104:105], v[8:9], v[104:105]
	v_pk_mul_f32 v[8:9], v[8:9], s[100:101] op_sel_hi:[1,0]
	v_pk_mul_f32 v[8:9], v[8:9], s[20:21] op_sel_hi:[1,0]
	v_exp_f32_e32 v16, v8
	v_exp_f32_e32 v17, v9
	v_pk_add_f32 v[14:15], v[14:15], s[22:23] op_sel_hi:[1,0]
	v_rcp_f32_e32 v14, v14
	v_rcp_f32_e32 v15, v15
	v_pk_mul_f32 v[12:13], v[116:117], v[12:13]
	v_cvt_pk_bf16_f32 v19, v12, v13
	ds_write_b16 v75, v19 offset:64
	ds_write_b16_d16_hi v75, v19 offset:96
	v_pk_mul_f32 v[2:3], v[86:87], s[98:99] op_sel_hi:[1,0]
	v_pk_mul_f32 v[2:3], v[86:87], v[2:3]
	v_pk_fma_f32 v[2:3], v[86:87], v[2:3], v[86:87]
	v_pk_mul_f32 v[2:3], v[2:3], s[100:101] op_sel_hi:[1,0]
	v_pk_mul_f32 v[2:3], v[2:3], s[20:21] op_sel_hi:[1,0]
	v_exp_f32_e32 v10, v2
	v_exp_f32_e32 v11, v3
	v_pk_add_f32 v[16:17], v[16:17], s[22:23] op_sel_hi:[1,0]
	v_rcp_f32_e32 v16, v16
	v_rcp_f32_e32 v17, v17
	v_pk_mul_f32 v[14:15], v[102:103], v[14:15]
	v_cvt_pk_bf16_f32 v20, v14, v15
	ds_write_b16 v75, v20 offset:512
	ds_write_b16_d16_hi v75, v20 offset:544
	v_pk_mul_f32 v[4:5], v[88:89], s[98:99] op_sel_hi:[1,0]
	v_pk_mul_f32 v[4:5], v[88:89], v[4:5]
	v_pk_fma_f32 v[4:5], v[88:89], v[4:5], v[88:89]
	v_pk_mul_f32 v[4:5], v[4:5], s[100:101] op_sel_hi:[1,0]
	v_pk_mul_f32 v[4:5], v[4:5], s[20:21] op_sel_hi:[1,0]
	v_exp_f32_e32 v12, v4
	v_exp_f32_e32 v13, v5
	v_pk_add_f32 v[10:11], v[10:11], s[22:23] op_sel_hi:[1,0]
	v_rcp_f32_e32 v10, v10
	v_rcp_f32_e32 v11, v11
	v_pk_mul_f32 v[16:17], v[104:105], v[16:17]
	v_cvt_pk_bf16_f32 v21, v16, v17
	ds_write_b16 v75, v21 offset:576
	ds_write_b16_d16_hi v75, v21 offset:608
	v_pk_mul_f32 v[6:7], v[70:71], s[98:99] op_sel_hi:[1,0]
	v_pk_mul_f32 v[6:7], v[70:71], v[6:7]
	v_pk_fma_f32 v[6:7], v[70:71], v[6:7], v[70:71]
	v_pk_mul_f32 v[6:7], v[6:7], s[100:101] op_sel_hi:[1,0]
	v_pk_mul_f32 v[6:7], v[6:7], s[20:21] op_sel_hi:[1,0]
	v_exp_f32_e32 v14, v6
	v_exp_f32_e32 v15, v7
	v_pk_add_f32 v[12:13], v[12:13], s[22:23] op_sel_hi:[1,0]
	v_rcp_f32_e32 v12, v12
	v_rcp_f32_e32 v13, v13
	v_pk_mul_f32 v[10:11], v[86:87], v[10:11]
	v_cvt_pk_bf16_f32 v18, v10, v11
	ds_write_b16 v75, v18 offset:1024
	ds_write_b16_d16_hi v75, v18 offset:1056
	v_pk_mul_f32 v[8:9], v[72:73], s[98:99] op_sel_hi:[1,0]
	v_pk_mul_f32 v[8:9], v[72:73], v[8:9]
	v_pk_fma_f32 v[8:9], v[72:73], v[8:9], v[72:73]
	v_pk_mul_f32 v[8:9], v[8:9], s[100:101] op_sel_hi:[1,0]
	v_pk_mul_f32 v[8:9], v[8:9], s[20:21] op_sel_hi:[1,0]
	v_exp_f32_e32 v16, v8
	v_exp_f32_e32 v17, v9
	v_pk_add_f32 v[14:15], v[14:15], s[22:23] op_sel_hi:[1,0]
	v_rcp_f32_e32 v14, v14
	v_rcp_f32_e32 v15, v15
	v_pk_mul_f32 v[12:13], v[88:89], v[12:13]
	v_cvt_pk_bf16_f32 v19, v12, v13
	ds_write_b16 v75, v19 offset:1088
	ds_write_b16_d16_hi v75, v19 offset:1120
	v_pk_mul_f32 v[2:3], v[62:63], s[98:99] op_sel_hi:[1,0]
	v_pk_mul_f32 v[2:3], v[62:63], v[2:3]
	v_pk_fma_f32 v[2:3], v[62:63], v[2:3], v[62:63]
	v_pk_mul_f32 v[2:3], v[2:3], s[100:101] op_sel_hi:[1,0]
	v_pk_mul_f32 v[2:3], v[2:3], s[20:21] op_sel_hi:[1,0]
	v_exp_f32_e32 v10, v2
	v_exp_f32_e32 v11, v3
	v_pk_add_f32 v[16:17], v[16:17], s[22:23] op_sel_hi:[1,0]
	v_rcp_f32_e32 v16, v16
	v_rcp_f32_e32 v17, v17
	v_pk_mul_f32 v[14:15], v[70:71], v[14:15]
	v_cvt_pk_bf16_f32 v20, v14, v15
	ds_write_b16 v75, v20 offset:1536
	ds_write_b16_d16_hi v75, v20 offset:1568
	v_pk_mul_f32 v[4:5], v[64:65], s[98:99] op_sel_hi:[1,0]
	v_pk_mul_f32 v[4:5], v[64:65], v[4:5]
	v_pk_fma_f32 v[4:5], v[64:65], v[4:5], v[64:65]
	v_pk_mul_f32 v[4:5], v[4:5], s[100:101] op_sel_hi:[1,0]
	v_pk_mul_f32 v[4:5], v[4:5], s[20:21] op_sel_hi:[1,0]
	v_exp_f32_e32 v12, v4
	v_exp_f32_e32 v13, v5
	v_pk_add_f32 v[10:11], v[10:11], s[22:23] op_sel_hi:[1,0]
	v_rcp_f32_e32 v10, v10
	v_rcp_f32_e32 v11, v11
	v_pk_mul_f32 v[16:17], v[72:73], v[16:17]
	v_cvt_pk_bf16_f32 v21, v16, v17
	ds_write_b16 v75, v21 offset:1600
	ds_write_b16_d16_hi v75, v21 offset:1632
	v_pk_mul_f32 v[6:7], v[54:55], s[98:99] op_sel_hi:[1,0]
	v_pk_mul_f32 v[6:7], v[54:55], v[6:7]
	v_pk_fma_f32 v[6:7], v[54:55], v[6:7], v[54:55]
	v_pk_mul_f32 v[6:7], v[6:7], s[100:101] op_sel_hi:[1,0]
	v_pk_mul_f32 v[6:7], v[6:7], s[20:21] op_sel_hi:[1,0]
	v_exp_f32_e32 v14, v6
	v_exp_f32_e32 v15, v7
	v_pk_add_f32 v[12:13], v[12:13], s[22:23] op_sel_hi:[1,0]
	v_rcp_f32_e32 v12, v12
	v_rcp_f32_e32 v13, v13
	v_pk_mul_f32 v[10:11], v[62:63], v[10:11]
	v_cvt_pk_bf16_f32 v18, v10, v11
	ds_write_b16 v75, v18 offset:2048
	ds_write_b16_d16_hi v75, v18 offset:2080
	v_pk_mul_f32 v[8:9], v[56:57], s[98:99] op_sel_hi:[1,0]
	v_pk_mul_f32 v[8:9], v[56:57], v[8:9]
	v_pk_fma_f32 v[8:9], v[56:57], v[8:9], v[56:57]
	v_pk_mul_f32 v[8:9], v[8:9], s[100:101] op_sel_hi:[1,0]
	v_pk_mul_f32 v[8:9], v[8:9], s[20:21] op_sel_hi:[1,0]
	v_exp_f32_e32 v16, v8
	v_exp_f32_e32 v17, v9
	v_pk_add_f32 v[14:15], v[14:15], s[22:23] op_sel_hi:[1,0]
	v_rcp_f32_e32 v14, v14
	v_rcp_f32_e32 v15, v15
	v_pk_mul_f32 v[12:13], v[64:65], v[12:13]
	v_cvt_pk_bf16_f32 v19, v12, v13
	ds_write_b16 v75, v19 offset:2112
	ds_write_b16_d16_hi v75, v19 offset:2144
	v_pk_mul_f32 v[2:3], v[46:47], s[98:99] op_sel_hi:[1,0]
	v_pk_mul_f32 v[2:3], v[46:47], v[2:3]
	v_pk_fma_f32 v[2:3], v[46:47], v[2:3], v[46:47]
	v_pk_mul_f32 v[2:3], v[2:3], s[100:101] op_sel_hi:[1,0]
	v_pk_mul_f32 v[2:3], v[2:3], s[20:21] op_sel_hi:[1,0]
	v_exp_f32_e32 v10, v2
	v_exp_f32_e32 v11, v3
	v_pk_add_f32 v[16:17], v[16:17], s[22:23] op_sel_hi:[1,0]
	v_rcp_f32_e32 v16, v16
	v_rcp_f32_e32 v17, v17
	v_pk_mul_f32 v[14:15], v[54:55], v[14:15]
	v_cvt_pk_bf16_f32 v20, v14, v15
	ds_write_b16 v75, v20 offset:2560
	ds_write_b16_d16_hi v75, v20 offset:2592
	v_pk_mul_f32 v[4:5], v[48:49], s[98:99] op_sel_hi:[1,0]
	v_pk_mul_f32 v[4:5], v[48:49], v[4:5]
	v_pk_fma_f32 v[4:5], v[48:49], v[4:5], v[48:49]
	v_pk_mul_f32 v[4:5], v[4:5], s[100:101] op_sel_hi:[1,0]
	v_pk_mul_f32 v[4:5], v[4:5], s[20:21] op_sel_hi:[1,0]
	v_exp_f32_e32 v12, v4
	v_exp_f32_e32 v13, v5
	v_pk_add_f32 v[10:11], v[10:11], s[22:23] op_sel_hi:[1,0]
	v_rcp_f32_e32 v10, v10
	v_rcp_f32_e32 v11, v11
	v_pk_mul_f32 v[16:17], v[56:57], v[16:17]
	v_cvt_pk_bf16_f32 v21, v16, v17
	ds_write_b16 v75, v21 offset:2624
	ds_write_b16_d16_hi v75, v21 offset:2656
	v_pk_mul_f32 v[6:7], v[38:39], s[98:99] op_sel_hi:[1,0]
	v_pk_mul_f32 v[6:7], v[38:39], v[6:7]
	v_pk_fma_f32 v[6:7], v[38:39], v[6:7], v[38:39]
	v_pk_mul_f32 v[6:7], v[6:7], s[100:101] op_sel_hi:[1,0]
	v_pk_mul_f32 v[6:7], v[6:7], s[20:21] op_sel_hi:[1,0]
	v_exp_f32_e32 v14, v6
	v_exp_f32_e32 v15, v7
	v_pk_add_f32 v[12:13], v[12:13], s[22:23] op_sel_hi:[1,0]
	v_rcp_f32_e32 v12, v12
	v_rcp_f32_e32 v13, v13
	v_pk_mul_f32 v[10:11], v[46:47], v[10:11]
	v_cvt_pk_bf16_f32 v18, v10, v11
	ds_write_b16 v75, v18 offset:3072
	ds_write_b16_d16_hi v75, v18 offset:3104
	v_pk_mul_f32 v[8:9], v[40:41], s[98:99] op_sel_hi:[1,0]
	v_pk_mul_f32 v[8:9], v[40:41], v[8:9]
	v_pk_fma_f32 v[8:9], v[40:41], v[8:9], v[40:41]
	v_pk_mul_f32 v[8:9], v[8:9], s[100:101] op_sel_hi:[1,0]
	v_pk_mul_f32 v[8:9], v[8:9], s[20:21] op_sel_hi:[1,0]
	v_exp_f32_e32 v16, v8
	v_exp_f32_e32 v17, v9
	v_pk_add_f32 v[14:15], v[14:15], s[22:23] op_sel_hi:[1,0]
	v_rcp_f32_e32 v14, v14
	v_rcp_f32_e32 v15, v15
	v_pk_mul_f32 v[12:13], v[48:49], v[12:13]
	v_cvt_pk_bf16_f32 v19, v12, v13
	ds_write_b16 v75, v19 offset:3136
	ds_write_b16_d16_hi v75, v19 offset:3168
	v_pk_mul_f32 v[2:3], v[110:111], s[98:99] op_sel_hi:[1,0]
	v_pk_mul_f32 v[2:3], v[110:111], v[2:3]
	v_pk_fma_f32 v[2:3], v[110:111], v[2:3], v[110:111]
	v_pk_mul_f32 v[2:3], v[2:3], s[100:101] op_sel_hi:[1,0]
	v_pk_mul_f32 v[2:3], v[2:3], s[20:21] op_sel_hi:[1,0]
	v_exp_f32_e32 v10, v2
	v_exp_f32_e32 v11, v3
	v_pk_add_f32 v[16:17], v[16:17], s[22:23] op_sel_hi:[1,0]
	v_rcp_f32_e32 v16, v16
	v_rcp_f32_e32 v17, v17
	v_pk_mul_f32 v[14:15], v[38:39], v[14:15]
	v_cvt_pk_bf16_f32 v20, v14, v15
	ds_write_b16 v75, v20 offset:3584
	ds_write_b16_d16_hi v75, v20 offset:3616
	v_pk_mul_f32 v[4:5], v[112:113], s[98:99] op_sel_hi:[1,0]
	v_pk_mul_f32 v[4:5], v[112:113], v[4:5]
	v_pk_fma_f32 v[4:5], v[112:113], v[4:5], v[112:113]
	v_pk_mul_f32 v[4:5], v[4:5], s[100:101] op_sel_hi:[1,0]
	v_pk_mul_f32 v[4:5], v[4:5], s[20:21] op_sel_hi:[1,0]
	v_exp_f32_e32 v12, v4
	v_exp_f32_e32 v13, v5
	v_pk_add_f32 v[10:11], v[10:11], s[22:23] op_sel_hi:[1,0]
	v_rcp_f32_e32 v10, v10
	v_rcp_f32_e32 v11, v11
	v_pk_mul_f32 v[16:17], v[40:41], v[16:17]
	v_cvt_pk_bf16_f32 v21, v16, v17
	ds_write_b16 v75, v21 offset:3648
	ds_write_b16_d16_hi v75, v21 offset:3680
	v_pk_mul_f32 v[6:7], v[94:95], s[98:99] op_sel_hi:[1,0]
	v_pk_mul_f32 v[6:7], v[94:95], v[6:7]
	v_pk_fma_f32 v[6:7], v[94:95], v[6:7], v[94:95]
	v_pk_mul_f32 v[6:7], v[6:7], s[100:101] op_sel_hi:[1,0]
	v_pk_mul_f32 v[6:7], v[6:7], s[20:21] op_sel_hi:[1,0]
	v_exp_f32_e32 v14, v6
	v_exp_f32_e32 v15, v7
	v_pk_add_f32 v[12:13], v[12:13], s[22:23] op_sel_hi:[1,0]
	v_rcp_f32_e32 v12, v12
	v_rcp_f32_e32 v13, v13
	v_pk_mul_f32 v[10:11], v[110:111], v[10:11]
	v_cvt_pk_bf16_f32 v18, v10, v11
	ds_write_b16 v75, v18 offset:4096
	ds_write_b16_d16_hi v75, v18 offset:4128
	v_pk_mul_f32 v[8:9], v[96:97], s[98:99] op_sel_hi:[1,0]
	v_pk_mul_f32 v[8:9], v[96:97], v[8:9]
	v_pk_fma_f32 v[8:9], v[96:97], v[8:9], v[96:97]
	v_pk_mul_f32 v[8:9], v[8:9], s[100:101] op_sel_hi:[1,0]
	v_pk_mul_f32 v[8:9], v[8:9], s[20:21] op_sel_hi:[1,0]
	v_exp_f32_e32 v16, v8
	v_exp_f32_e32 v17, v9
	v_pk_add_f32 v[14:15], v[14:15], s[22:23] op_sel_hi:[1,0]
	v_rcp_f32_e32 v14, v14
	v_rcp_f32_e32 v15, v15
	v_pk_mul_f32 v[12:13], v[112:113], v[12:13]
	v_cvt_pk_bf16_f32 v19, v12, v13
	ds_write_b16 v75, v19 offset:4160
	ds_write_b16_d16_hi v75, v19 offset:4192
	v_pk_mul_f32 v[2:3], v[78:79], s[98:99] op_sel_hi:[1,0]
	v_pk_mul_f32 v[2:3], v[78:79], v[2:3]
	v_pk_fma_f32 v[2:3], v[78:79], v[2:3], v[78:79]
	v_pk_mul_f32 v[2:3], v[2:3], s[100:101] op_sel_hi:[1,0]
	v_pk_mul_f32 v[2:3], v[2:3], s[20:21] op_sel_hi:[1,0]
	v_exp_f32_e32 v10, v2
	v_exp_f32_e32 v11, v3
	v_pk_add_f32 v[16:17], v[16:17], s[22:23] op_sel_hi:[1,0]
	v_rcp_f32_e32 v16, v16
	v_rcp_f32_e32 v17, v17
	v_pk_mul_f32 v[14:15], v[94:95], v[14:15]
	v_cvt_pk_bf16_f32 v20, v14, v15
	ds_write_b16 v75, v20 offset:4608
	ds_write_b16_d16_hi v75, v20 offset:4640
	v_pk_mul_f32 v[4:5], v[80:81], s[98:99] op_sel_hi:[1,0]
	v_pk_mul_f32 v[4:5], v[80:81], v[4:5]
	v_pk_fma_f32 v[4:5], v[80:81], v[4:5], v[80:81]
	v_pk_mul_f32 v[4:5], v[4:5], s[100:101] op_sel_hi:[1,0]
	v_pk_mul_f32 v[4:5], v[4:5], s[20:21] op_sel_hi:[1,0]
	v_exp_f32_e32 v12, v4
	v_exp_f32_e32 v13, v5
	v_pk_add_f32 v[10:11], v[10:11], s[22:23] op_sel_hi:[1,0]
	v_rcp_f32_e32 v10, v10
	v_rcp_f32_e32 v11, v11
	v_pk_mul_f32 v[16:17], v[96:97], v[16:17]
	v_cvt_pk_bf16_f32 v21, v16, v17
	ds_write_b16 v75, v21 offset:4672
	ds_write_b16_d16_hi v75, v21 offset:4704
	v_pk_mul_f32 v[6:7], v[66:67], s[98:99] op_sel_hi:[1,0]
	v_pk_mul_f32 v[6:7], v[66:67], v[6:7]
	v_pk_fma_f32 v[6:7], v[66:67], v[6:7], v[66:67]
	v_pk_mul_f32 v[6:7], v[6:7], s[100:101] op_sel_hi:[1,0]
	v_pk_mul_f32 v[6:7], v[6:7], s[20:21] op_sel_hi:[1,0]
	v_exp_f32_e32 v14, v6
	v_exp_f32_e32 v15, v7
	v_pk_add_f32 v[12:13], v[12:13], s[22:23] op_sel_hi:[1,0]
	v_rcp_f32_e32 v12, v12
	v_rcp_f32_e32 v13, v13
	v_pk_mul_f32 v[10:11], v[78:79], v[10:11]
	v_cvt_pk_bf16_f32 v18, v10, v11
	ds_write_b16 v75, v18 offset:5120
	ds_write_b16_d16_hi v75, v18 offset:5152
	v_pk_mul_f32 v[8:9], v[68:69], s[98:99] op_sel_hi:[1,0]
	v_pk_mul_f32 v[8:9], v[68:69], v[8:9]
	v_pk_fma_f32 v[8:9], v[68:69], v[8:9], v[68:69]
	v_pk_mul_f32 v[8:9], v[8:9], s[100:101] op_sel_hi:[1,0]
	v_pk_mul_f32 v[8:9], v[8:9], s[20:21] op_sel_hi:[1,0]
	v_exp_f32_e32 v16, v8
	v_exp_f32_e32 v17, v9
	v_pk_add_f32 v[14:15], v[14:15], s[22:23] op_sel_hi:[1,0]
	v_rcp_f32_e32 v14, v14
	v_rcp_f32_e32 v15, v15
	v_pk_mul_f32 v[12:13], v[80:81], v[12:13]
	v_cvt_pk_bf16_f32 v19, v12, v13
	ds_write_b16 v75, v19 offset:5184
	ds_write_b16_d16_hi v75, v19 offset:5216
	v_pk_mul_f32 v[2:3], v[58:59], s[98:99] op_sel_hi:[1,0]
	v_pk_mul_f32 v[2:3], v[58:59], v[2:3]
	v_pk_fma_f32 v[2:3], v[58:59], v[2:3], v[58:59]
	v_pk_mul_f32 v[2:3], v[2:3], s[100:101] op_sel_hi:[1,0]
	v_pk_mul_f32 v[2:3], v[2:3], s[20:21] op_sel_hi:[1,0]
	v_exp_f32_e32 v10, v2
	v_exp_f32_e32 v11, v3
	v_pk_add_f32 v[16:17], v[16:17], s[22:23] op_sel_hi:[1,0]
	v_rcp_f32_e32 v16, v16
	v_rcp_f32_e32 v17, v17
	v_pk_mul_f32 v[14:15], v[66:67], v[14:15]
	v_cvt_pk_bf16_f32 v20, v14, v15
	ds_write_b16 v75, v20 offset:5632
	ds_write_b16_d16_hi v75, v20 offset:5664
	v_pk_mul_f32 v[4:5], v[60:61], s[98:99] op_sel_hi:[1,0]
	v_pk_mul_f32 v[4:5], v[60:61], v[4:5]
	v_pk_fma_f32 v[4:5], v[60:61], v[4:5], v[60:61]
	v_pk_mul_f32 v[4:5], v[4:5], s[100:101] op_sel_hi:[1,0]
	v_pk_mul_f32 v[4:5], v[4:5], s[20:21] op_sel_hi:[1,0]
	v_exp_f32_e32 v12, v4
	v_exp_f32_e32 v13, v5
	v_pk_add_f32 v[10:11], v[10:11], s[22:23] op_sel_hi:[1,0]
	v_rcp_f32_e32 v10, v10
	v_rcp_f32_e32 v11, v11
	v_pk_mul_f32 v[16:17], v[68:69], v[16:17]
	v_cvt_pk_bf16_f32 v21, v16, v17
	ds_write_b16 v75, v21 offset:5696
	ds_write_b16_d16_hi v75, v21 offset:5728
	v_pk_mul_f32 v[6:7], v[50:51], s[98:99] op_sel_hi:[1,0]
	v_pk_mul_f32 v[6:7], v[50:51], v[6:7]
	v_pk_fma_f32 v[6:7], v[50:51], v[6:7], v[50:51]
	v_pk_mul_f32 v[6:7], v[6:7], s[100:101] op_sel_hi:[1,0]
	v_pk_mul_f32 v[6:7], v[6:7], s[20:21] op_sel_hi:[1,0]
	v_exp_f32_e32 v14, v6
	v_exp_f32_e32 v15, v7
	v_pk_add_f32 v[12:13], v[12:13], s[22:23] op_sel_hi:[1,0]
	v_rcp_f32_e32 v12, v12
	v_rcp_f32_e32 v13, v13
	v_pk_mul_f32 v[10:11], v[58:59], v[10:11]
	v_cvt_pk_bf16_f32 v18, v10, v11
	ds_write_b16 v75, v18 offset:6144
	ds_write_b16_d16_hi v75, v18 offset:6176
	v_pk_mul_f32 v[8:9], v[52:53], s[98:99] op_sel_hi:[1,0]
	v_pk_mul_f32 v[8:9], v[52:53], v[8:9]
	v_pk_fma_f32 v[8:9], v[52:53], v[8:9], v[52:53]
	v_pk_mul_f32 v[8:9], v[8:9], s[100:101] op_sel_hi:[1,0]
	v_pk_mul_f32 v[8:9], v[8:9], s[20:21] op_sel_hi:[1,0]
	v_exp_f32_e32 v16, v8
	v_exp_f32_e32 v17, v9
	v_pk_add_f32 v[14:15], v[14:15], s[22:23] op_sel_hi:[1,0]
	v_rcp_f32_e32 v14, v14
	v_rcp_f32_e32 v15, v15
	v_pk_mul_f32 v[12:13], v[60:61], v[12:13]
	v_cvt_pk_bf16_f32 v19, v12, v13
	ds_write_b16 v75, v19 offset:6208
	ds_write_b16_d16_hi v75, v19 offset:6240
	v_pk_mul_f32 v[2:3], v[42:43], s[98:99] op_sel_hi:[1,0]
	v_pk_mul_f32 v[2:3], v[42:43], v[2:3]
	v_pk_fma_f32 v[2:3], v[42:43], v[2:3], v[42:43]
	v_pk_mul_f32 v[2:3], v[2:3], s[100:101] op_sel_hi:[1,0]
	v_pk_mul_f32 v[2:3], v[2:3], s[20:21] op_sel_hi:[1,0]
	v_exp_f32_e32 v10, v2
	v_exp_f32_e32 v11, v3
	v_pk_add_f32 v[16:17], v[16:17], s[22:23] op_sel_hi:[1,0]
	v_rcp_f32_e32 v16, v16
	v_rcp_f32_e32 v17, v17
	v_pk_mul_f32 v[14:15], v[50:51], v[14:15]
	v_cvt_pk_bf16_f32 v20, v14, v15
	ds_write_b16 v75, v20 offset:6656
	ds_write_b16_d16_hi v75, v20 offset:6688
	v_pk_mul_f32 v[4:5], v[44:45], s[98:99] op_sel_hi:[1,0]
	v_pk_mul_f32 v[4:5], v[44:45], v[4:5]
	v_pk_fma_f32 v[4:5], v[44:45], v[4:5], v[44:45]
	v_pk_mul_f32 v[4:5], v[4:5], s[100:101] op_sel_hi:[1,0]
	v_pk_mul_f32 v[4:5], v[4:5], s[20:21] op_sel_hi:[1,0]
	v_exp_f32_e32 v12, v4
	v_exp_f32_e32 v13, v5
	v_pk_add_f32 v[10:11], v[10:11], s[22:23] op_sel_hi:[1,0]
	v_rcp_f32_e32 v10, v10
	v_rcp_f32_e32 v11, v11
	v_pk_mul_f32 v[16:17], v[52:53], v[16:17]
	v_cvt_pk_bf16_f32 v21, v16, v17
	ds_write_b16 v75, v21 offset:6720
	ds_write_b16_d16_hi v75, v21 offset:6752
	v_pk_mul_f32 v[6:7], v[34:35], s[98:99] op_sel_hi:[1,0]
	v_pk_mul_f32 v[6:7], v[34:35], v[6:7]
	v_pk_fma_f32 v[6:7], v[34:35], v[6:7], v[34:35]
	v_pk_mul_f32 v[6:7], v[6:7], s[100:101] op_sel_hi:[1,0]
	v_pk_mul_f32 v[6:7], v[6:7], s[20:21] op_sel_hi:[1,0]
	v_exp_f32_e32 v14, v6
	v_exp_f32_e32 v15, v7
	v_pk_add_f32 v[12:13], v[12:13], s[22:23] op_sel_hi:[1,0]
	v_rcp_f32_e32 v12, v12
	v_rcp_f32_e32 v13, v13
	v_pk_mul_f32 v[10:11], v[42:43], v[10:11]
	v_cvt_pk_bf16_f32 v18, v10, v11
	ds_write_b16 v75, v18 offset:7168
	ds_write_b16_d16_hi v75, v18 offset:7200
	v_pk_mul_f32 v[8:9], v[36:37], s[98:99] op_sel_hi:[1,0]
	v_pk_mul_f32 v[8:9], v[36:37], v[8:9]
	v_pk_fma_f32 v[8:9], v[36:37], v[8:9], v[36:37]
	v_pk_mul_f32 v[8:9], v[8:9], s[100:101] op_sel_hi:[1,0]
	v_pk_mul_f32 v[8:9], v[8:9], s[20:21] op_sel_hi:[1,0]
	v_exp_f32_e32 v16, v8
	v_exp_f32_e32 v17, v9
	v_pk_add_f32 v[14:15], v[14:15], s[22:23] op_sel_hi:[1,0]
	v_rcp_f32_e32 v14, v14
	v_rcp_f32_e32 v15, v15
	v_pk_mul_f32 v[12:13], v[44:45], v[12:13]
	v_cvt_pk_bf16_f32 v19, v12, v13
	ds_write_b16 v75, v19 offset:7232
	ds_write_b16_d16_hi v75, v19 offset:7264
	v_pk_add_f32 v[16:17], v[16:17], s[22:23] op_sel_hi:[1,0]
	v_rcp_f32_e32 v16, v16
	v_rcp_f32_e32 v17, v17
	v_pk_mul_f32 v[14:15], v[34:35], v[14:15]
	v_cvt_pk_bf16_f32 v20, v14, v15
	ds_write_b16 v75, v20 offset:7680
	ds_write_b16_d16_hi v75, v20 offset:7712
	v_pk_mul_f32 v[16:17], v[36:37], v[16:17]
	v_cvt_pk_bf16_f32 v21, v16, v17
	ds_write_b16 v75, v21 offset:7744
	ds_write_b16_d16_hi v75, v21 offset:7776
	s_waitcnt lgkmcnt(0)
	ds_read_b128 v[34:37], v76
	ds_read_b128 v[38:41], v76 offset:1024
	ds_read_b128 v[42:45], v76 offset:2048
	ds_read_b128 v[46:49], v76 offset:3072
	ds_read_b128 v[50:53], v76 offset:4096
	ds_read_b128 v[54:57], v76 offset:5120
	ds_read_b128 v[58:61], v76 offset:6144
	ds_read_b128 v[62:65], v76 offset:7168
	s_lshl_b32 s24, s91, 4
	s_add_i32 s25, s24, s47
	s_lshl_b32 s25, s25, 10
	s_add_u32 s48, s18, s25
	s_addc_u32 s49, s19, 0
	s_add_i32 s25, s24, s47
	s_addk_i32 s25, 512
	s_lshl_b32 s25, s25, 10
	s_add_u32 s50, s18, s25
	s_addc_u32 s51, s19, 0
	s_add_i32 s25, s24, s47
	s_addk_i32 s25, 1024
	s_lshl_b32 s25, s25, 10
	s_add_u32 s52, s18, s25
	s_addc_u32 s53, s19, 0
	s_add_i32 s25, s24, s47
	s_addk_i32 s25, 1536
	s_lshl_b32 s25, s25, 10
	s_add_u32 s54, s18, s25
	s_addc_u32 s55, s19, 0
	s_add_i32 s25, s24, s14
	s_lshl_b32 s25, s25, 10
	s_add_u32 s56, s18, s25
	s_addc_u32 s57, s19, 0
	s_add_i32 s25, s24, s14
	s_addk_i32 s25, 512
	s_lshl_b32 s25, s25, 10
	s_add_u32 s58, s18, s25
	s_addc_u32 s59, s19, 0
	s_add_i32 s25, s24, s14
	s_addk_i32 s25, 1024
	s_lshl_b32 s25, s25, 10
	s_add_u32 s60, s18, s25
	s_addc_u32 s61, s19, 0
	s_add_i32 s25, s24, s14
	s_addk_i32 s25, 1536
	s_lshl_b32 s25, s25, 10
	s_add_u32 s62, s18, s25
	s_addc_u32 s63, s19, 0
	s_waitcnt lgkmcnt(7)
	global_store_dwordx4 v77, v[34:37], s[48:49]
	s_waitcnt lgkmcnt(6)
	global_store_dwordx4 v77, v[38:41], s[50:51]
	s_waitcnt lgkmcnt(5)
	global_store_dwordx4 v77, v[42:45], s[52:53]
	s_waitcnt lgkmcnt(4)
	global_store_dwordx4 v77, v[46:49], s[54:55]
	s_waitcnt lgkmcnt(3)
	global_store_dwordx4 v77, v[50:53], s[56:57]
	s_waitcnt lgkmcnt(2)
	global_store_dwordx4 v77, v[54:57], s[58:59]
	s_waitcnt lgkmcnt(1)
	global_store_dwordx4 v77, v[58:61], s[60:61]
	s_waitcnt lgkmcnt(0)
	global_store_dwordx4 v77, v[62:65], s[62:63]
.Ls5_epi_tail:
	s_andn2_b64 vcc, exec, s[76:77]
	s_waitcnt lgkmcnt(0)
	s_barrier
	s_movk_i32 s91, 0x80
	s_mov_b64 s[52:53], 0
	s_cbranch_vccz .LBB0_653

	.amdhsa_kernel _Z9hymba_fwd4Args
		.amdhsa_group_segment_fixed_size 0
		.amdhsa_private_segment_fixed_size 0
		.amdhsa_kernarg_size 472
		.amdhsa_user_sgpr_count 2
		.amdhsa_user_sgpr_dispatch_ptr 0
		.amdhsa_user_sgpr_queue_ptr 0
		.amdhsa_user_sgpr_kernarg_segment_ptr 1
		.amdhsa_user_sgpr_dispatch_id 0
		.amdhsa_user_sgpr_kernarg_preload_length 0
		.amdhsa_user_sgpr_kernarg_preload_offset 0
		.amdhsa_user_sgpr_private_segment_size 0
		.amdhsa_uses_dynamic_stack 0
		.amdhsa_enable_private_segment 0
		.amdhsa_system_sgpr_workgroup_id_x 1
		.amdhsa_system_sgpr_workgroup_id_y 0
		.amdhsa_system_sgpr_workgroup_id_z 0
		.amdhsa_system_sgpr_workgroup_info 0
		.amdhsa_system_vgpr_workitem_id 2
		.amdhsa_next_free_vgpr 248
		.amdhsa_next_free_sgpr 102
		.amdhsa_accum_offset 248
		.amdhsa_reserve_vcc 1
		.amdhsa_float_round_mode_32 0
		.amdhsa_float_round_mode_16_64 0
		.amdhsa_float_denorm_mode_32 3
		.amdhsa_float_denorm_mode_16_64 3
		.amdhsa_dx10_clamp 1
		.amdhsa_ieee_mode 1
		.amdhsa_fp16_overflow 0
		.amdhsa_tg_split 0
		.amdhsa_exception_fp_ieee_invalid_op 0
		.amdhsa_exception_fp_denorm_src 0
		.amdhsa_exception_fp_ieee_div_zero 0
		.amdhsa_exception_fp_ieee_overflow 0
		.amdhsa_exception_fp_ieee_underflow 0
		.amdhsa_exception_fp_ieee_inexact 0
		.amdhsa_exception_int_div_zero 0
	.end_amdhsa_kernel

amdhsa.kernels:
  - .agpr_count:     0
    .args:
      - .offset:         0
        .size:           216
        .value_kind:     by_value
      - .offset:         216
        .size:           4
        .value_kind:     hidden_block_count_x
      - .offset:         220
        .size:           4
        .value_kind:     hidden_block_count_y
      - .offset:         224
        .size:           4
        .value_kind:     hidden_block_count_z
      - .offset:         228
        .size:           2
        .value_kind:     hidden_group_size_x
      - .offset:         230
        .size:           2
        .value_kind:     hidden_group_size_y
      - .offset:         232
        .size:           2
        .value_kind:     hidden_group_size_z
      - .offset:         234
        .size:           2
        .value_kind:     hidden_remainder_x
      - .offset:         236
        .size:           2
        .value_kind:     hidden_remainder_y
      - .offset:         238
        .size:           2
        .value_kind:     hidden_remainder_z
      - .offset:         256
        .size:           8
        .value_kind:     hidden_global_offset_x
      - .offset:         264
        .size:           8
        .value_kind:     hidden_global_offset_y
      - .offset:         272
        .size:           8
        .value_kind:     hidden_global_offset_z
      - .offset:         280
        .size:           2
        .value_kind:     hidden_grid_dims
      - .offset:         304
        .size:           8
        .value_kind:     hidden_multigrid_sync_arg
      - .offset:         336
        .size:           4
        .value_kind:     hidden_dynamic_lds_size
    .group_segment_fixed_size: 0
    .kernarg_segment_align: 8
    .kernarg_segment_size: 472
    .language:       OpenCL C
    .language_version:
      - 2
      - 0
    .max_flat_workgroup_size: 512
    .name:           _Z9hymba_fwd4Args
    .private_segment_fixed_size: 0
    .sgpr_count:     108
    .sgpr_spill_count: 223
    .symbol:         _Z9hymba_fwd4Args.kd
    .uniform_work_group_size: 1
    .uses_dynamic_stack: false
    .vgpr_count:     248
    .vgpr_spill_count: 0
    .wavefront_size: 64
